# attention unit prologues: wait before the first QK MFMA relaxed to its own operands (late K2/V1 DMAs stay in flight)
# baseline (speedup 1.0000x reference)
.Ltb_u1_b:
	s_ashr_i32 s11, s6, 6
	s_lshl_b32 s10, s43, 4
	s_lshl_b32 s26, s11, 2
	v_bfe_u32 v233, v237, 4, 2
	s_and_b32 s60, s10, 0xfffff000
	v_or_b32_e32 v52, s26, v233
	s_waitcnt vmcnt(0)
	v_add_u32_e32 v2, s60, v52
	v_ashrrev_i32_e32 v3, 31, v2
	v_readlane_b32 s18, v252, 31
	v_bitop3_b32 v0, s26, v237, v233 bitop3:0x36
	v_lshlrev_b64 v[2:3], 12, v[2:3]
	v_readlane_b32 s19, v252, 32
	s_and_b32 s46, s43, 15
	s_lshl_b32 s84, s28, 8
	v_lshl_add_u64 v[2:3], s[18:19], 0, v[2:3]
	v_lshlrev_b32_e32 v0, 4, v0
	s_xor_b32 s17, s46, 31
	s_and_b32 s2, s11, 3
	v_lshl_add_u64 v[2:3], v[2:3], 0, s[84:85]
	v_and_b32_e32 v0, 0xf0, v0
	s_lshl_b32 s27, s11, 3
	v_bfe_u32 v53, v237, 3, 3
	s_lshl_b32 s21, s17, 7
	s_lshl_b32 s22, s2, 5
	s_lshl_b32 s18, s28, 7
	v_lshl_add_u64 v[2:3], v[2:3], 0, v[0:1]
	v_or_b32_e32 v0, s27, v53
	s_or_b32 s20, s22, s21
	v_lshrrev_b32_e32 v54, 1, v0
	v_add_u32_e32 v4, s18, v0
	v_and_b32_e32 v235, 31, v237
	v_xor_b32_e32 v6, v54, v237
	v_ashrrev_i32_e32 v5, 31, v4
	v_readlane_b32 s36, v252, 39
	s_or_b32 s10, s20, s60
	v_lshlrev_b64 v[4:5], 15, v[4:5]
	v_readlane_b32 s37, v252, 40
	v_lshlrev_b32_e32 v0, 4, v6
	v_or_b32_e32 v6, s10, v235
	v_lshl_add_u64 v[4:5], s[36:37], 0, v[4:5]
	v_ashrrev_i32_e32 v7, 31, v6
	v_readlane_b32 s36, v252, 17
	s_ashr_i32 s3, s6, 8
	v_lshlrev_b64 v[6:7], 12, v[6:7]
	v_readlane_b32 s37, v252, 18
	s_ashr_i32 s61, s60, 31
	v_bfe_u32 v234, v237, 5, 1
	v_lshl_add_u64 v[6:7], s[36:37], 0, v[6:7]
	s_lshl_b32 s36, s3, 6
	v_lshl_add_u64 v[4:5], s[60:61], 1, v[4:5]
	v_and_b32_e32 v0, 0x70, v0
	v_lshl_add_u64 v[6:7], v[6:7], 0, s[84:85]
	s_ashr_i32 s37, s36, 31
	v_lshl_add_u64 v[4:5], v[4:5], 0, v[0:1]
	v_lshl_add_u64 v[6:7], s[36:37], 1, v[6:7]
	v_lshlrev_b32_e32 v0, 4, v234
	v_lshl_add_u64 v[6:7], v[6:7], 0, v[0:1]
	global_load_dwordx4 v[146:149], v[6:7], off nt
	global_load_dwordx4 v[150:153], v[6:7], off offset:32 nt
	global_load_dwordx4 v[154:157], v[6:7], off offset:64 nt
	global_load_dwordx4 v[158:161], v[6:7], off offset:96 nt
	s_lshl_b32 s11, s11, 10
	s_add_i32 s11, s11, 0
	s_mov_b32 m0, s11
	s_mov_b64 s[36:37], 0x20000
	global_load_lds_dwordx4 v[2:3], off
	v_lshl_add_u64 v[8:9], v[2:3], 0, s[36:37]
	s_add_i32 m0, s11, 0x2000
	s_mov_b64 s[36:37], 0x40000
	global_load_lds_dwordx4 v[8:9], off
	s_add_i32 m0, s11, 0x4000
	v_lshl_add_u64 v[8:9], v[2:3], 0, s[36:37]
	s_mov_b64 s[36:37], 0x60000
	global_load_lds_dwordx4 v[8:9], off
	v_lshl_add_u64 v[8:9], v[2:3], 0, s[36:37]
	s_add_i32 m0, s11, 0x6000
	s_mov_b64 s[36:37], 0x200000
	global_load_lds_dwordx4 v[8:9], off
	s_add_i32 m0, s11, 0xc000
	v_lshl_add_u64 v[8:9], v[4:5], 0, s[36:37]
	global_load_lds_dwordx4 v[4:5], off
	s_add_i32 m0, s11, 0xe000
	s_mov_b64 s[36:37], 0xa0000
	global_load_lds_dwordx4 v[8:9], off
	s_add_i32 m0, s11, 0x8000
	v_lshl_add_u64 v[8:9], v[2:3], 0, s[34:35]
	global_load_lds_dwordx4 v[8:9], off
	v_lshl_add_u64 v[2:3], v[2:3], 0, s[36:37]
	s_add_i32 m0, s11, 0xa000
	s_mov_b64 s[36:37], 0x80
	global_load_lds_dwordx4 v[2:3], off
	s_add_i32 m0, s11, 0x10000
	v_lshl_add_u64 v[2:3], v[4:5], 0, s[36:37]
	s_mov_b64 s[36:37], 0x200080
	global_load_lds_dwordx4 v[2:3], off
	v_lshl_add_u64 v[2:3], v[4:5], 0, s[36:37]
	s_add_i32 m0, s11, 0x12000
	v_and_b32_e32 v0, 19, v237
	global_load_lds_dwordx4 v[2:3], off
	v_lshlrev_b32_e32 v2, 1, v237
	v_lshrrev_b32_e32 v35, 1, v34
	v_and_or_b32 v0, v2, 8, v0
	v_and_b32_e32 v22, 4, v35
	v_or_b32_e32 v2, v0, v22
	v_lshl_or_b32 v45, s3, 3, v234
	v_lshlrev_b32_e32 v44, 8, v2
	v_bitop3_b32 v2, v2, v45, 15 bitop3:0x6c
	v_lshl_add_u32 v239, v2, 4, v44
	s_waitcnt vmcnt(4)
	s_barrier
	v_add_u32_e32 v6, 0, v239
	v_bitop3_b32 v0, v0, 15, v22 bitop3:0xc8
	ds_read_b128 v[2:5], v6
	ds_read_b128 v[18:21], v6 offset:8192
	v_bitop3_b32 v22, v45, v0, 2 bitop3:0x36
	v_lshl_add_u32 v240, v22, 4, v44
	v_add_u32_e32 v40, 0, v240
	ds_read_b128 v[36:39], v40
	s_waitcnt lgkmcnt(0)
	v_mfma_f32_32x32x16_bf16 v[2:17], v[2:5], v[146:149], 0
	ds_read_b128 v[40:43], v40 offset:8192
	v_bfe_u32 v34, v34, 1, 3
	v_bitop3_b32 v57, v234, v34, 2 bitop3:0x36
	v_bitop3_b32 v58, v234, v34, 4 bitop3:0x36
	v_bitop3_b32 v59, v234, v34, 6 bitop3:0x36
	s_and_b32 s56, s42, 0xfffff000
	s_add_i32 s26, s26, s56
	v_mfma_f32_32x32x16_bf16 v[18:33], v[18:21], v[146:149], 0
	s_lshr_b32 s16, s43, 4
	s_and_b32 s16, s16, 15
	s_lshl_b32 s36, s16, 7
	s_lshl_b32 s37, s16, 8
	s_add_i32 s27, s27, s36
	s_ashr_i32 s57, s56, 31
	s_lshl_b64 s[44:45], s[56:57], 1
	v_mfma_f32_32x32x16_bf16 v[2:17], v[36:39], v[150:153], v[2:17]
	v_bitop3_b32 v36, v45, v0, 4 bitop3:0x36
	v_lshl_add_u32 v241, v36, 4, v44
	v_add_u32_e32 v46, 0, v241
	ds_read_b128 v[36:39], v46
	v_bitop3_b32 v0, v45, v0, 6 bitop3:0x36
	v_lshl_add_u32 v243, v0, 4, v44
	v_add_u32_e32 v0, 0, v243
	s_waitcnt lgkmcnt(1)
	v_mfma_f32_32x32x16_bf16 v[18:33], v[40:43], v[150:153], v[18:33]
	ds_read_b128 v[40:43], v46 offset:8192
	v_lshlrev_b32_e32 v236, 3, v234
	s_mov_b32 s84, s85
	v_bitop3_b32 v56, v35, v234, 7 bitop3:0x6c
	s_mov_b32 s86, s85
	s_mov_b32 s87, s85
	s_mov_b32 s88, s85
	s_waitcnt lgkmcnt(1)
	v_mfma_f32_32x32x16_bf16 v[2:17], v[36:39], v[154:157], v[2:17]
	ds_read_b128 v[36:39], v0
	s_mov_b32 s89, s85
	s_mov_b32 s90, s85
	s_mov_b32 s91, s85
	s_mov_b32 s92, s85
	s_mov_b32 s93, s85
	s_mov_b32 s94, s85
	s_waitcnt lgkmcnt(1)
	v_mfma_f32_32x32x16_bf16 v[18:33], v[40:43], v[154:157], v[18:33]
	ds_read_b128 v[40:43], v0 offset:8192
	s_mov_b32 s95, s85
	s_mov_b32 s96, s85
	s_mov_b32 s97, s85
	s_mov_b32 s98, s85
	s_mov_b32 s99, s85
	s_lshl_b32 s16, s17, 1
	s_waitcnt lgkmcnt(1)
	v_mfma_f32_32x32x16_bf16 v[2:17], v[36:39], v[158:161], v[2:17]
	v_lshlrev_b32_e32 v55, 7, v235
	s_lshr_b32 s19, s20, 6
	s_add_i32 s17, s16, 2
	s_add_i32 s19, s19, 1
	v_lshl_or_b32 v244, v56, 4, v55
	v_lshl_or_b32 v245, v57, 4, v55
	v_lshl_or_b32 v246, v58, 4, v55
	s_waitcnt lgkmcnt(0)
	v_mfma_f32_32x32x16_bf16 v[18:33], v[40:43], v[158:161], v[18:33]
	s_nop 2
	v_max_f32_e32 v34, v3, v3
	v_lshl_or_b32 v247, v59, 4, v55
	s_mov_b32 s23, 1
	v_and_b32_e32 v238, 63, v237
	s_mov_b32 s31, 0x8000
	s_min_u32 s19, s17, s19
	s_addk_i32 s20, 0xff50
	s_nop 1
	v_max_f32_e32 v0, v19, v19
	v_max_f32_e32 v0, v34, v0
	v_max3_f32 v0, v2, v18, v0
	v_max3_f32 v34, v20, v5, v21
	v_max3_f32 v0, v0, v4, v34
	v_max3_f32 v34, v22, v7, v23
	v_max3_f32 v0, v0, v6, v34
	v_max3_f32 v34, v24, v9, v25
	v_max3_f32 v0, v0, v8, v34
	v_max3_f32 v34, v26, v11, v27
	v_max3_f32 v0, v0, v10, v34
	v_max3_f32 v34, v28, v13, v29
	v_max3_f32 v0, v0, v12, v34
	v_max3_f32 v34, v30, v15, v31
	v_max3_f32 v0, v0, v14, v34
	v_max3_f32 v34, v32, v17, v33
	v_max3_f32 v0, v0, v16, v34
	v_mov_b32_e32 v34, v0
	s_nop 1
	v_permlane32_swap_b32_e32 v0, v34
	v_max_f32_e32 v34, v34, v34
	v_max_f32_e32 v0, v0, v0
	v_max_f32_e32 v213, v0, v34
	v_sub_f32_e32 v0, v2, v213
	v_exp_f32_e32 v60, v0
	v_sub_f32_e32 v0, v18, v213
	v_exp_f32_e32 v61, v0
	v_sub_f32_e32 v0, v3, v213
	v_sub_f32_e32 v2, v19, v213
	v_exp_f32_e32 v0, v0
	v_exp_f32_e32 v2, v2
	v_add_f32_e32 v3, v61, v60
	v_mov_b64_e32 v[34:35], s[84:85]
	v_cvt_pk_bf16_f32 v162, v60, v0
	v_pk_add_f32 v[18:19], v[2:3], v[0:1]
	v_sub_f32_e32 v3, v4, v213
	v_sub_f32_e32 v4, v20, v213
	v_pk_add_f32 v[18:19], v[18:19], v[18:19] op_sel_hi:[0,1]
	v_exp_f32_e32 v62, v4
	v_sub_f32_e32 v4, v5, v213
	v_exp_f32_e32 v3, v3
	v_exp_f32_e32 v18, v4
	v_sub_f32_e32 v4, v21, v213
	v_exp_f32_e32 v4, v4
	v_add_f32_e32 v5, v62, v3
	v_sub_u32_e32 v0, 7, v237
	v_cvt_pk_bf16_f32 v178, v61, v2
	v_pk_add_f32 v[20:21], v[4:5], v[18:19]
	v_sub_f32_e32 v5, v6, v213
	v_sub_f32_e32 v6, v22, v213
	v_pk_add_f32 v[20:21], v[20:21], v[20:21] op_sel_hi:[0,1]
	v_exp_f32_e32 v19, v6
	v_sub_f32_e32 v6, v7, v213
	v_exp_f32_e32 v5, v5
	v_exp_f32_e32 v20, v6
	v_sub_f32_e32 v6, v23, v213
	v_exp_f32_e32 v6, v6
	v_add_f32_e32 v7, v19, v5
	v_and_b32_e32 v0, 3, v0
	v_mov_b32_e32 v2, s33
	v_pk_add_f32 v[22:23], v[6:7], v[20:21]
	v_sub_f32_e32 v7, v8, v213
	v_sub_f32_e32 v8, v24, v213
	v_pk_add_f32 v[22:23], v[22:23], v[22:23] op_sel_hi:[0,1]
	v_exp_f32_e32 v21, v8
	v_sub_f32_e32 v8, v9, v213
	v_exp_f32_e32 v7, v7
	v_exp_f32_e32 v22, v8
	v_sub_f32_e32 v8, v25, v213
	v_exp_f32_e32 v8, v8
	v_add_f32_e32 v9, v21, v7
	s_movk_i32 s33, 0x510
	v_mad_u32_u24 v0, v0, s33, v2
	v_pk_add_f32 v[24:25], v[8:9], v[22:23]
	v_sub_f32_e32 v9, v10, v213
	v_sub_f32_e32 v10, v26, v213
	v_pk_add_f32 v[24:25], v[24:25], v[24:25] op_sel_hi:[0,1]
	v_exp_f32_e32 v23, v10
	v_sub_f32_e32 v10, v11, v213
	v_exp_f32_e32 v9, v9
	v_exp_f32_e32 v24, v10
	v_sub_f32_e32 v10, v27, v213
	v_exp_f32_e32 v10, v10
	v_add_f32_e32 v11, v23, v9
	v_or_b32_e32 v2, s26, v233
	v_cvt_pk_bf16_f32 v163, v3, v18
	v_pk_add_f32 v[26:27], v[10:11], v[24:25]
	v_sub_f32_e32 v11, v12, v213
	v_sub_f32_e32 v12, v28, v213
	v_pk_add_f32 v[26:27], v[26:27], v[26:27] op_sel_hi:[0,1]
	v_exp_f32_e32 v25, v12
	v_sub_f32_e32 v12, v13, v213
	v_exp_f32_e32 v11, v11
	v_exp_f32_e32 v26, v12
	v_sub_f32_e32 v12, v29, v213
	v_exp_f32_e32 v12, v12
	v_add_f32_e32 v13, v25, v11
	v_ashrrev_i32_e32 v3, 31, v2
	v_lshlrev_b64 v[214:215], 12, v[2:3]
	v_pk_add_f32 v[28:29], v[12:13], v[26:27]
	v_sub_f32_e32 v13, v14, v213
	v_sub_f32_e32 v14, v30, v213
	v_pk_add_f32 v[28:29], v[28:29], v[28:29] op_sel_hi:[0,1]
	v_exp_f32_e32 v27, v14
	v_sub_f32_e32 v14, v15, v213
	v_exp_f32_e32 v13, v13
	v_exp_f32_e32 v28, v14
	v_sub_f32_e32 v14, v31, v213
	v_exp_f32_e32 v14, v14
	v_sub_f32_e32 v15, v16, v213
	v_exp_f32_e32 v63, v15
	v_sub_f32_e32 v15, v32, v213
	v_exp_f32_e32 v32, v15
	v_add_f32_e32 v15, v27, v13
	v_pk_add_f32 v[30:31], v[14:15], v[28:29]
	v_bitop3_b32 v2, v52, 15, v237 bitop3:0x48
	v_pk_add_f32 v[30:31], v[30:31], v[30:31] op_sel_hi:[0,1]
	v_sub_f32_e32 v15, v17, v213
	v_lshlrev_b32_e32 v2, 4, v2
	v_exp_f32_e32 v30, v15
	v_sub_f32_e32 v15, v33, v213
	v_or3_b32 v214, v214, s37, v2
	v_or_b32_e32 v2, s27, v53
	v_exp_f32_e32 v50, v15
	v_ashrrev_i32_e32 v3, 31, v2
	v_cvt_pk_bf16_f32 v179, v62, v4
	v_lshlrev_b64 v[2:3], 15, v[2:3]
	v_bitop3_b32 v4, v54, 7, v237 bitop3:0x48
	v_lshl_or_b32 v2, v4, 4, v2
	v_add_f32_e32 v51, v32, v63
	v_lshl_add_u64 v[216:217], v[2:3], 0, s[44:45]
	v_sub_u32_e32 v2, v236, v235
	v_mov_b64_e32 v[48:49], s[98:99]
	v_pk_add_f32 v[16:17], v[50:51], v[30:31]
	v_subrev_u32_e32 v2, s22, v2
	v_mov_b64_e32 v[36:37], s[86:87]
	v_mov_b64_e32 v[38:39], s[88:89]
	v_mov_b64_e32 v[40:41], s[90:91]
	v_mov_b64_e32 v[42:43], s[92:93]
	v_mov_b64_e32 v[44:45], s[94:95]
	v_mov_b64_e32 v[46:47], s[96:97]
	v_xor_b32_e32 v66, 0x80000000, v213
	v_add_f32_e32 v242, v16, v17
	v_cvt_pk_bf16_f32 v164, v5, v20
	v_cvt_pk_bf16_f32 v165, v7, v22
	v_cvt_pk_bf16_f32 v170, v9, v24
	v_cvt_pk_bf16_f32 v171, v11, v26
	v_cvt_pk_bf16_f32 v172, v13, v28
	v_cvt_pk_bf16_f32 v173, v63, v30
	v_cvt_pk_bf16_f32 v180, v19, v6
	v_cvt_pk_bf16_f32 v181, v21, v8
	v_cvt_pk_bf16_f32 v186, v23, v10
	v_cvt_pk_bf16_f32 v187, v25, v12
	v_cvt_pk_bf16_f32 v188, v27, v14
	v_cvt_pk_bf16_f32 v189, v32, v50
	v_subrev_u32_e32 v248, s21, v2
	v_mov_b64_e32 v[64:65], v[48:49]
	v_mov_b64_e32 v[18:19], v[34:35]
	v_mov_b64_e32 v[2:3], v[34:35]
	v_readlane_b32 s94, v255, 10
	v_readlane_b32 s90, v255, 12
	v_mov_b32_e32 v67, v66
	v_mov_b32_e32 v68, v66
	v_mov_b32_e32 v69, v66
	v_mov_b32_e32 v70, v66
	v_mov_b32_e32 v71, v66
	v_mov_b32_e32 v72, v66
	v_mov_b32_e32 v73, v66
	v_mov_b32_e32 v74, v66
	v_mov_b32_e32 v75, v66
	v_mov_b32_e32 v76, v66
	v_mov_b32_e32 v77, v66
	v_mov_b32_e32 v78, v66
	v_mov_b32_e32 v79, v66
	v_mov_b32_e32 v80, v66
	v_mov_b32_e32 v81, v66
	s_mov_b32 s21, 0
	v_mov_b32_e32 v166, 0
	v_mov_b32_e32 v167, 0
	v_mov_b32_e32 v168, 0
	v_mov_b32_e32 v169, 0
	v_mov_b32_e32 v174, 0
	v_mov_b32_e32 v175, 0
	v_mov_b32_e32 v176, 0
	v_mov_b32_e32 v177, 0
	v_mov_b32_e32 v182, 0
	v_mov_b32_e32 v183, 0
	v_mov_b32_e32 v184, 0
	v_mov_b32_e32 v185, 0
	v_mov_b32_e32 v190, 0
	v_mov_b32_e32 v191, 0
	v_mov_b32_e32 v192, 0
	v_mov_b32_e32 v193, 0
	v_mov_b64_e32 v[62:63], v[46:47]
	v_mov_b64_e32 v[60:61], v[44:45]
	v_mov_b64_e32 v[58:59], v[42:43]
	v_mov_b64_e32 v[56:57], v[40:41]
	v_mov_b64_e32 v[54:55], v[38:39]
	v_mov_b64_e32 v[52:53], v[36:37]
	v_mov_b64_e32 v[50:51], v[34:35]
	v_mov_b64_e32 v[20:21], v[36:37]
	v_mov_b64_e32 v[22:23], v[38:39]
	v_mov_b64_e32 v[24:25], v[40:41]
	v_mov_b64_e32 v[26:27], v[42:43]
	v_mov_b64_e32 v[28:29], v[44:45]
	v_mov_b64_e32 v[30:31], v[46:47]
	v_mov_b64_e32 v[32:33], v[48:49]
	v_mov_b64_e32 v[4:5], v[36:37]
	v_mov_b64_e32 v[6:7], v[38:39]
	v_mov_b64_e32 v[8:9], v[40:41]
	v_mov_b64_e32 v[10:11], v[42:43]
	v_mov_b64_e32 v[12:13], v[44:45]
	v_mov_b64_e32 v[14:15], v[46:47]
	v_mov_b64_e32 v[16:17], v[48:49]
	s_mov_b32 s33, 0x4000
	s_mov_b32 s48, 0
	s_mov_b32 s49, 0
	s_movk_i32 s92, 0x6e
	s_movk_i32 s93, 0xd0
	s_mov_b32 s57, 0x41000000
	v_readlane_b32 s95, v255, 11
	v_readlane_b32 s91, v255, 13
	s_add_u32 s80, s8, 0xd0c0000
	s_addc_u32 s81, s9, 0
	s_add_u32 s62, s8, 0xd0e0000
	s_addc_u32 s63, s9, 0
	s_add_u32 s96, s8, 0x15000100
	s_addc_u32 s97, s9, 0
	s_add_u32 s58, s8, 0x15200100
	s_addc_u32 s59, s9, 0
	s_add_u32 s50, s8, 0xd100000
	s_addc_u32 s51, s9, 0
	s_add_u32 s4, s8, 0xd120000
	s_addc_u32 s5, s9, 0
	s_add_u32 s0, s8, 0x15000180
	s_addc_u32 s1, s9, 0
	s_add_u32 s52, s8, 0x15200180
	s_addc_u32 s53, s9, 0
	v_add_u32_e32 v244, 0x8000, v244
	v_add_u32_e32 v245, 0x8000, v245
	v_add_u32_e32 v246, 0x8000, v246
	v_add_u32_e32 v247, 0x8000, v247
	ds_read_b128 v[202:205], v239 offset:16384
	ds_read_b128 v[194:197], v239 offset:24576
	ds_read_b128 v[198:201], v240 offset:16384

.LBB0_261:
	s_and_b32 s2, s2, 3
	s_lshl_b32 s11, s46, 7
	s_lshl_b32 s28, s2, 5
	s_or_b32 s16, s28, s11
	v_and_b32_e32 v235, 31, v237
	s_or_b32 s11, s16, s60
	v_or_b32_e32 v6, s11, v235
	v_ashrrev_i32_e32 v7, 31, v6
	v_readlane_b32 s18, v252, 17
	s_ashr_i32 s6, s3, 8
	v_lshlrev_b64 v[6:7], 12, v[6:7]
	v_readlane_b32 s19, v252, 18
	v_and_b32_e32 v238, 63, v237
	v_lshrrev_b32_e32 v234, 5, v238
	v_lshl_add_u64 v[6:7], s[18:19], 0, v[6:7]
	s_lshl_b32 s18, s6, 6
	v_lshl_add_u64 v[6:7], v[6:7], 0, s[84:85]
	s_ashr_i32 s19, s18, 31
	v_lshl_add_u64 v[6:7], s[18:19], 1, v[6:7]
	v_lshlrev_b32_e32 v0, 4, v234
	v_lshl_add_u64 v[6:7], v[6:7], 0, v[0:1]
	global_load_dwordx4 v[146:149], v[6:7], off nt
	global_load_dwordx4 v[150:153], v[6:7], off offset:32 nt
	global_load_dwordx4 v[154:157], v[6:7], off offset:64 nt
	global_load_dwordx4 v[158:161], v[6:7], off offset:96 nt
	s_mov_b64 s[18:19], 0x80
	s_add_i32 m0, s10, 0x10000
	v_lshl_add_u64 v[8:9], v[4:5], 0, s[18:19]
	s_mov_b64 s[18:19], 0x200080
	v_lshl_add_u64 v[4:5], v[4:5], 0, s[18:19]
	global_load_lds_dwordx4 v[8:9], off
	s_add_i32 m0, s10, 0x12000
	v_and_b32_e32 v0, 19, v237
	global_load_lds_dwordx4 v[4:5], off
	v_lshlrev_b32_e32 v3, 1, v237
	v_lshrrev_b32_e32 v38, 1, v2
	v_and_or_b32 v0, v3, 8, v0
	v_and_b32_e32 v22, 4, v38
	v_or_b32_e32 v2, v0, v22
	v_lshl_or_b32 v37, s6, 3, v234
	v_lshlrev_b32_e32 v39, 8, v2
	v_bitop3_b32 v2, v2, v37, 15 bitop3:0x6c
	v_lshl_add_u32 v239, v2, 4, v39
	v_add_u32_e32 v18, 0, v239
	s_waitcnt vmcnt(4)
	s_barrier
	ds_read_b128 v[2:5], v18
	v_bitop3_b32 v0, v0, 15, v22 bitop3:0xc8
	v_bitop3_b32 v22, v37, v0, 2 bitop3:0x36
	v_lshl_add_u32 v240, v22, 4, v39
	v_add_u32_e32 v44, 0, v240
	ds_read_b128 v[40:43], v44
	ds_read_b128 v[18:21], v18 offset:8192
	s_mov_b64 s[26:27], -1
	s_cmpk_lt_u32 s16, 0xb0
	s_waitcnt vmcnt(2) lgkmcnt(0)
	v_mfma_f32_32x32x16_bf16 v[2:17], v[2:5], v[146:149], 0
	v_mfma_f32_32x32x16_bf16 v[2:17], v[40:43], v[150:153], v[2:17]
	ds_read_b128 v[40:43], v44 offset:8192
	v_bitop3_b32 v44, v37, v0, 4 bitop3:0x36
	v_lshl_add_u32 v241, v44, 4, v39
	v_add_u32_e32 v44, 0, v241
	v_bitop3_b32 v0, v37, v0, 6 bitop3:0x36
	v_lshl_add_u32 v242, v0, 4, v39
	v_add_u32_e32 v0, 0, v242
	v_mfma_f32_32x32x16_bf16 v[18:33], v[18:21], v[146:149], 0
	v_or_b32_e32 v37, s16, v235
	ds_read_b128 v[194:197], v44
	ds_read_b128 v[198:201], v44 offset:8192
	ds_read_b128 v[202:205], v0
	ds_read_b128 v[206:209], v0 offset:8192
	s_waitcnt lgkmcnt(4)
	v_mfma_f32_32x32x16_bf16 v[18:33], v[40:43], v[150:153], v[18:33]
	s_waitcnt lgkmcnt(3)
	v_mfma_f32_32x32x16_bf16 v[2:17], v[194:197], v[154:157], v[2:17]
	s_waitcnt lgkmcnt(2)
	v_mfma_f32_32x32x16_bf16 v[18:33], v[198:201], v[154:157], v[18:33]
	s_waitcnt lgkmcnt(1)
	v_mfma_f32_32x32x16_bf16 v[2:17], v[202:205], v[158:161], v[2:17]
	s_waitcnt lgkmcnt(0)
	v_mfma_f32_32x32x16_bf16 v[18:33], v[206:209], v[158:161], v[18:33]
	s_cbranch_scc1 .LBB0_263
	v_or_b32_e32 v0, s16, v235
	s_mov_b64 s[26:27], 0
